# RG-LRU tile staging: the five row-piece loads issued together with counted waits instead of load-wait-write five times
# speedup vs baseline: 1.0126x; 1.0012x over previous
; __device__ __forceinline__ void rg_item(CArgs& A, int l, const bf16* P, bf16* Y, int b, int h, int cg, float* ldsf, int tid) {
;     ...
;             { const int t0 = qtr * 512 + tl * 32;
; #pragma unroll
;               for (int p = 0; p < 5; ++p) { const int rw = (lane >> 3) + 8 * p, ts = t0 - 3 + rw; u32x4 v = (u32x4){0u, 0u, 0u, 0u};
;                   if (rw < 35 && ts >= 0) v = *(const u32x4*)(P + ((size_t)b * SEQ + ts) * NP + PC_RGX + h * 64 + (lane & 7) * 8);
;                   if (rw < 35) *(u32x4*)(xs + rw * 144 + (lane & 7) * 16) = v; }
;               asm volatile("s_waitcnt lgkmcnt(0)" ::: "memory"); }
.LBB0_272:
	v_add_u32_e32 v8, -32, v86
	v_mov_b32_e32 v9, v0
	v_cmp_lt_i32_e32 vcc, -1, v8
	v_mov_b32_e32 v230, 0
	v_mov_b32_e32 v231, 0
	v_mov_b32_e32 v232, 0
	v_mov_b32_e32 v233, 0
	s_and_saveexec_b64 s[4:5], vcc
	v_lshl_add_u64 v[4:5], s[58:59], 0, v[8:9]
	v_mad_u64_u32 v[6:7], s[0:1], v4, s79, v[78:79]
	v_mad_i32_i24 v7, v5, s79, v7
	global_load_dwordx4 v[230:233], v[6:7], off
	s_or_b64 exec, exec, s[4:5]
	v_add_u32_e32 v8, -24, v86
	v_mov_b32_e32 v9, v0
	v_cmp_lt_i32_e32 vcc, -1, v8
	v_mov_b32_e32 v234, 0
	v_mov_b32_e32 v235, 0
	v_mov_b32_e32 v236, 0
	v_mov_b32_e32 v237, 0
	s_and_saveexec_b64 s[4:5], vcc
	v_lshl_add_u64 v[4:5], s[58:59], 0, v[8:9]
	v_mad_u64_u32 v[6:7], s[0:1], v4, s79, v[78:79]
	v_mad_i32_i24 v7, v5, s79, v7
	global_load_dwordx4 v[234:237], v[6:7], off
	s_or_b64 exec, exec, s[4:5]
	v_add_u32_e32 v8, -16, v86
	v_mov_b32_e32 v9, v0
	v_cmp_lt_i32_e32 vcc, -1, v8
	v_mov_b32_e32 v238, 0
	v_mov_b32_e32 v239, 0
	v_mov_b32_e32 v240, 0
	v_mov_b32_e32 v241, 0
	s_and_saveexec_b64 s[4:5], vcc
	v_lshl_add_u64 v[4:5], s[58:59], 0, v[8:9]
	v_mad_u64_u32 v[6:7], s[0:1], v4, s79, v[78:79]
	v_mad_i32_i24 v7, v5, s79, v7
	global_load_dwordx4 v[238:241], v[6:7], off
	s_or_b64 exec, exec, s[4:5]
	v_add_u32_e32 v8, -8, v86
	v_mov_b32_e32 v9, v0
	v_cmp_lt_i32_e32 vcc, -1, v8
	v_mov_b32_e32 v242, 0
	v_mov_b32_e32 v243, 0
	v_mov_b32_e32 v244, 0
	v_mov_b32_e32 v245, 0
	s_and_saveexec_b64 s[4:5], vcc
	v_lshl_add_u64 v[4:5], s[58:59], 0, v[8:9]
	v_mad_u64_u32 v[6:7], s[0:1], v4, s79, v[78:79]
	v_mad_i32_i24 v7, v5, s79, v7
	global_load_dwordx4 v[242:245], v[6:7], off
	s_or_b64 exec, exec, s[4:5]
	v_cmp_lt_i32_e32 vcc, -1, v86
	v_mov_b32_e32 v87, v0
	v_mov_b32_e32 v246, 0
	v_mov_b32_e32 v247, 0
	v_mov_b32_e32 v248, 0
	v_mov_b32_e32 v249, 0
	s_and_b64 s[0:1], s[46:47], vcc
	s_and_saveexec_b64 s[4:5], s[0:1]
	v_lshl_add_u64 v[4:5], s[58:59], 0, v[86:87]
	v_mad_u64_u32 v[6:7], s[0:1], v4, s79, v[78:79]
	v_mad_i32_i24 v7, v5, s79, v7
	global_load_dwordx4 v[246:249], v[6:7], off
	s_or_b64 exec, exec, s[4:5]
	s_waitcnt vmcnt(4)
	ds_write_b128 v99, v[230:233]
	s_waitcnt vmcnt(3)
	ds_write_b128 v99, v[234:237] offset:1152
	s_waitcnt vmcnt(2)
	ds_write_b128 v99, v[238:241] offset:2304
	s_waitcnt vmcnt(1)
	ds_write_b128 v99, v[242:245] offset:3456
	s_and_saveexec_b64 s[4:5], s[46:47]
	s_waitcnt vmcnt(0)
	ds_write_b128 v99, v[246:249] offset:4608
